# P1: non-temporal stores for the late-consumed outputs (GL/GA gates, V^T) to keep UX/UG cache-resident for the RG-LRU phase
# speedup vs baseline: 1.0057x; 1.0057x over previous
; __device__ __forceinline__ u32x4 pack8(f32x4 a, f32x4 b) { u32x4 w; w.x = cvt_pk(a[0], a[1]); w.y = cvt_pk(a[2], a[3]); w.z = cvt_pk(b[0], b[1]); w.w = cvt_pk(b[2], b[3]); return w; }
;     __device__ __forceinline__ void operator()(EPI_ARGS) const {
;     ...
;         if (u.kind == 1) {
; #pragma unroll
;             for (int ai = 0; ai < 2; ++ai)
; #pragma unroll
;                 for (int m = 0; m < 4; ++m) { bf16_t* rowp = VT + (size_t)(row0 + ai * 128 + m * 16) * MT + colt;
; #pragma unroll
;                     for (int bj = 0; bj < 2; ++bj) { const u32x4 w = pack8(acc[ai][bj][m][0], acc[ai][bj][m][1]);
;                         bf16_t* g16 = rowp + bj * 128 - (fq & 1) * 8;
;                         u32x2 lo2 = {w.x, w.y}, hi2 = {w.z, w.w};
;                         *(u32x2*)(g16 + ((fq & 1) ? 4 : 0)) = lo2; *(u32x2*)(g16 + ((fq & 1) ? 12 : 8)) = hi2; } }
;             return;
.LBB0_215:
	v_ashrrev_i32_e32 v143, 31, v142
	v_readlane_b32 s0, v247, 43
	v_ashrrev_i32_e32 v145, 31, v144
	v_lshlrev_b64 v[148:149], 15, v[142:143]
	v_readlane_b32 s1, v247, 44
	v_bfe_u32 v150, v136, 4, 1
	v_lshlrev_b64 v[144:145], 1, v[144:145]
	v_lshl_add_u64 v[148:149], s[0:1], 0, v[148:149]
	v_cmp_eq_u32_e32 vcc, 0, v150
	v_lshl_add_u64 v[148:149], v[148:149], 0, v[144:145]
	v_lshlrev_b32_e32 v143, 4, v150
	v_lshlrev_b32_e32 v136, 3, v150
	v_cndmask_b32_e64 v146, 24, 16, vcc
	v_sub_co_u32_e32 v150, vcc, v148, v143
	v_mov_b32_e32 v147, v137
	s_nop 0
	v_subbrev_co_u32_e32 v151, vcc, 0, v149, vcc
	v_cvt_pk_bf16_f32 v124, v124, v125
	v_cvt_pk_bf16_f32 v125, v126, v127
	v_cvt_pk_bf16_f32 v120, v120, v121
	v_cvt_pk_bf16_f32 v121, v122, v123
	v_lshl_add_u64 v[122:123], v[150:151], 0, v[136:137]
	global_store_dwordx2 v[122:123], v[124:125], off nt
	v_lshl_add_u64 v[124:125], v[150:151], 0, v[146:147]
	v_cvt_pk_bf16_f32 v112, v112, v113
	v_cvt_pk_bf16_f32 v113, v114, v115
	v_cvt_pk_bf16_f32 v104, v104, v105
	global_store_dwordx2 v[124:125], v[120:121], off nt
	v_cvt_pk_bf16_f32 v105, v106, v107
	global_store_dwordx2 v[122:123], v[112:113], off offset:256 nt
	global_store_dwordx2 v[124:125], v[104:105], off offset:256 nt
	v_or_b32_e32 v104, 16, v142
	v_ashrrev_i32_e32 v105, 31, v104
	v_lshlrev_b64 v[104:105], 15, v[104:105]
	v_lshl_add_u64 v[104:105], s[0:1], 0, v[104:105]
	v_lshl_add_u64 v[104:105], v[104:105], 0, v[144:145]
	v_sub_co_u32_e32 v104, vcc, v104, v143
	v_cvt_pk_bf16_f32 v106, v116, v117
	s_nop 0
	v_subbrev_co_u32_e32 v105, vcc, 0, v105, vcc
	v_cvt_pk_bf16_f32 v107, v118, v119
	v_cvt_pk_bf16_f32 v108, v108, v109
	v_cvt_pk_bf16_f32 v109, v110, v111
	v_lshl_add_u64 v[110:111], v[104:105], 0, v[136:137]
	v_lshl_add_u64 v[104:105], v[104:105], 0, v[146:147]
	v_cvt_pk_bf16_f32 v96, v96, v97
	v_cvt_pk_bf16_f32 v97, v98, v99
	v_cvt_pk_bf16_f32 v88, v88, v89
	global_store_dwordx2 v[110:111], v[106:107], off nt
	global_store_dwordx2 v[104:105], v[108:109], off nt
	v_cvt_pk_bf16_f32 v89, v90, v91
	global_store_dwordx2 v[110:111], v[96:97], off offset:256 nt
	global_store_dwordx2 v[104:105], v[88:89], off offset:256 nt
	v_or_b32_e32 v88, 32, v142
	v_ashrrev_i32_e32 v89, 31, v88
	v_lshlrev_b64 v[88:89], 15, v[88:89]
	v_lshl_add_u64 v[88:89], s[0:1], 0, v[88:89]
	v_lshl_add_u64 v[88:89], v[88:89], 0, v[144:145]
	v_sub_co_u32_e32 v88, vcc, v88, v143
	v_cvt_pk_bf16_f32 v90, v100, v101
	s_nop 0
	v_subbrev_co_u32_e32 v89, vcc, 0, v89, vcc
	v_cvt_pk_bf16_f32 v91, v102, v103
	v_cvt_pk_bf16_f32 v92, v92, v93
	v_cvt_pk_bf16_f32 v93, v94, v95
	v_lshl_add_u64 v[94:95], v[88:89], 0, v[136:137]
	v_lshl_add_u64 v[88:89], v[88:89], 0, v[146:147]
	v_cvt_pk_bf16_f32 v80, v80, v81
	v_cvt_pk_bf16_f32 v81, v82, v83
	v_cvt_pk_bf16_f32 v72, v72, v73
	global_store_dwordx2 v[94:95], v[90:91], off nt
	global_store_dwordx2 v[88:89], v[92:93], off nt
	v_cvt_pk_bf16_f32 v73, v74, v75
	global_store_dwordx2 v[94:95], v[80:81], off offset:256 nt
	global_store_dwordx2 v[88:89], v[72:73], off offset:256 nt
	v_or_b32_e32 v72, 48, v142
	v_ashrrev_i32_e32 v73, 31, v72
	v_lshlrev_b64 v[72:73], 15, v[72:73]
	v_lshl_add_u64 v[72:73], s[0:1], 0, v[72:73]
	v_lshl_add_u64 v[72:73], v[72:73], 0, v[144:145]
	v_sub_co_u32_e32 v72, vcc, v72, v143
	v_cvt_pk_bf16_f32 v74, v84, v85
	s_nop 0
	v_subbrev_co_u32_e32 v73, vcc, 0, v73, vcc
	v_cvt_pk_bf16_f32 v75, v86, v87
	v_cvt_pk_bf16_f32 v76, v76, v77
	v_cvt_pk_bf16_f32 v77, v78, v79
	v_lshl_add_u64 v[78:79], v[72:73], 0, v[136:137]
	v_lshl_add_u64 v[72:73], v[72:73], 0, v[146:147]
	v_cvt_pk_bf16_f32 v68, v68, v69
	v_cvt_pk_bf16_f32 v69, v70, v71
	v_cvt_pk_bf16_f32 v64, v64, v65
	v_cvt_pk_bf16_f32 v65, v66, v67
	s_mov_b64 s[0:1], 0x400000
	global_store_dwordx2 v[78:79], v[74:75], off nt
	global_store_dwordx2 v[72:73], v[76:77], off nt
	global_store_dwordx2 v[78:79], v[68:69], off offset:256 nt
	global_store_dwordx2 v[72:73], v[64:65], off offset:256 nt
	v_lshl_add_u64 v[64:65], v[148:149], 0, s[0:1]
	v_sub_co_u32_e32 v64, vcc, v64, v143
	v_cvt_pk_bf16_f32 v60, v60, v61
	s_nop 0
	v_subbrev_co_u32_e32 v65, vcc, 0, v65, vcc
	v_cvt_pk_bf16_f32 v61, v62, v63
	v_cvt_pk_bf16_f32 v56, v56, v57
	v_cvt_pk_bf16_f32 v57, v58, v59
	v_lshl_add_u64 v[58:59], v[64:65], 0, v[136:137]
	global_store_dwordx2 v[58:59], v[60:61], off nt
	v_lshl_add_u64 v[60:61], v[64:65], 0, v[146:147]
	v_cvt_pk_bf16_f32 v44, v44, v45
	v_cvt_pk_bf16_f32 v45, v46, v47
	v_cvt_pk_bf16_f32 v40, v40, v41
	v_cvt_pk_bf16_f32 v41, v42, v43
	s_mov_b64 s[0:1], 0x480000
	global_store_dwordx2 v[60:61], v[56:57], off nt
	global_store_dwordx2 v[58:59], v[44:45], off offset:256 nt
	global_store_dwordx2 v[60:61], v[40:41], off offset:256 nt
	v_lshl_add_u64 v[40:41], v[148:149], 0, s[0:1]
	v_sub_co_u32_e32 v40, vcc, v40, v143
	v_cvt_pk_bf16_f32 v42, v52, v53
	s_nop 0
	v_subbrev_co_u32_e32 v41, vcc, 0, v41, vcc
	v_cvt_pk_bf16_f32 v43, v54, v55
	v_cvt_pk_bf16_f32 v44, v48, v49
	v_cvt_pk_bf16_f32 v45, v50, v51
	v_lshl_add_u64 v[46:47], v[40:41], 0, v[136:137]
	v_lshl_add_u64 v[40:41], v[40:41], 0, v[146:147]
	v_cvt_pk_bf16_f32 v28, v28, v29
	v_cvt_pk_bf16_f32 v29, v30, v31
	v_cvt_pk_bf16_f32 v24, v24, v25
	v_cvt_pk_bf16_f32 v25, v26, v27
	s_mov_b64 s[0:1], 0x500000
	global_store_dwordx2 v[46:47], v[42:43], off nt
	global_store_dwordx2 v[40:41], v[44:45], off nt
	global_store_dwordx2 v[46:47], v[28:29], off offset:256 nt
	global_store_dwordx2 v[40:41], v[24:25], off offset:256 nt
	v_lshl_add_u64 v[24:25], v[148:149], 0, s[0:1]
	v_sub_co_u32_e32 v24, vcc, v24, v143
	v_cvt_pk_bf16_f32 v26, v36, v37
	s_nop 0
	v_subbrev_co_u32_e32 v25, vcc, 0, v25, vcc
	v_cvt_pk_bf16_f32 v27, v38, v39
	v_cvt_pk_bf16_f32 v28, v32, v33
	v_cvt_pk_bf16_f32 v29, v34, v35
	v_lshl_add_u64 v[30:31], v[24:25], 0, v[136:137]
	v_lshl_add_u64 v[24:25], v[24:25], 0, v[146:147]
	v_cvt_pk_bf16_f32 v12, v12, v13
	v_cvt_pk_bf16_f32 v13, v14, v15
	v_cvt_pk_bf16_f32 v8, v8, v9
	v_cvt_pk_bf16_f32 v9, v10, v11
	s_mov_b64 s[0:1], 0x580000
	global_store_dwordx2 v[30:31], v[26:27], off nt
	global_store_dwordx2 v[24:25], v[28:29], off nt
	global_store_dwordx2 v[30:31], v[12:13], off offset:256 nt
	global_store_dwordx2 v[24:25], v[8:9], off offset:256 nt
	v_lshl_add_u64 v[8:9], v[148:149], 0, s[0:1]
	v_sub_co_u32_e32 v8, vcc, v8, v143
	v_cvt_pk_bf16_f32 v10, v20, v21
	s_nop 0
	v_subbrev_co_u32_e32 v9, vcc, 0, v9, vcc
	v_cvt_pk_bf16_f32 v11, v22, v23
	v_cvt_pk_bf16_f32 v12, v16, v17
	v_cvt_pk_bf16_f32 v13, v18, v19
	v_lshl_add_u64 v[14:15], v[8:9], 0, v[136:137]
	v_lshl_add_u64 v[8:9], v[8:9], 0, v[146:147]
	v_cvt_pk_bf16_f32 v4, v4, v5
	v_cvt_pk_bf16_f32 v5, v6, v7
	global_store_dwordx2 v[14:15], v[10:11], off nt
	global_store_dwordx2 v[8:9], v[12:13], off nt
	v_cvt_pk_bf16_f32 v0, v0, v1
	v_cvt_pk_bf16_f32 v1, v2, v3
	global_store_dwordx2 v[14:15], v[4:5], off offset:256 nt
	global_store_dwordx2 v[8:9], v[0:1], off offset:256 nt
	s_andn2_b64 vcc, exec, s[48:49]
	s_mov_b64 s[0:1], -1
	s_cbranch_vccnz .LBB0_98

; __device__ __forceinline__ float fsigmoid(float v) { return __builtin_amdgcn_rcpf(1.f + __builtin_amdgcn_exp2f(-LOG2E * v)); }
; __device__ __forceinline__ u32x4 pack8(f32x4 a, f32x4 b) { u32x4 w; w.x = cvt_pk(a[0], a[1]); w.y = cvt_pk(a[2], a[3]); w.z = cvt_pk(b[0], b[1]); w.w = cvt_pk(b[2], b[3]); return w; }
;     __device__ __forceinline__ void operator()(EPI_ARGS) const {
;         const int row0 = u.pm * 256 + wr * 64 + fr, colt = u.pn * 256 + wc * 32 + 8 * fq, sec = u.pn >> 2, cs = colt - sec * 1024;
;         bf16_t* base = sec ? GA : GL;
; #pragma unroll
;         for (int ai = 0; ai < 2; ++ai)
; #pragma unroll
;             for (int m = 0; m < 4; ++m) { bf16_t* rowp = base + (size_t)(row0 + ai * 128 + m * 16) * DM + cs;
; #pragma unroll
;                 for (int bj = 0; bj < 2; ++bj) { f32x4 v0 = acc[ai][bj][m][0] * 0.03125f, v1 = acc[ai][bj][m][1] * 0.03125f;
; #pragma unroll
;                     for (int e = 0; e < 4; ++e) { v0[e] = fsigmoid(v0[e]); v1[e] = fsigmoid(v1[e]); }
;                     *(u32x4*)(rowp + bj * 128) = pack8(v0, v1); } }
.LBB0_347:
	s_lshl_b32 s39, s46, 8
	v_mov_b32_e32 v128, v180
	s_add_i32 s39, s39, s30
	v_pk_mul_f32 v[120:121], v[120:121], s[36:37] op_sel_hi:[1,0]
	v_pk_mul_f32 v[124:125], v[124:125], s[36:37] op_sel_hi:[1,0]
	v_and_or_b32 v130, v128, 15, s39
	s_lshl_b32 s39, s3, 8
	v_mul_f32_e32 v120, 0xbfb8aa3b, v120
	s_and_b32 s39, s39, 0x300
	v_exp_f32_e32 v120, v120
	v_mul_f32_e32 v125, 0xbfb8aa3b, v125
	v_ashrrev_i32_e32 v128, 1, v128
	s_or_b32 s39, s39, s31
	v_readlane_b32 s46, v247, 31
	v_exp_f32_e32 v125, v125
	v_and_b32_e32 v128, -8, v128
	s_cmp_lt_u32 s3, 4
	v_readlane_b32 s47, v247, 32
	v_add_u32_e32 v128, s39, v128
	s_cselect_b32 s3, s67, s47
	s_cselect_b32 s39, s66, s46
	v_mov_b32_e32 v132, s39
	v_mov_b32_e32 v133, s3
	v_ashrrev_i32_e32 v129, 31, v128
	v_ashrrev_i32_e32 v131, 31, v130
	v_pk_mul_f32 v[126:127], v[126:127], s[36:37] op_sel_hi:[1,0]
	v_add_f32_e32 v120, 1.0, v120
	v_mul_f32_e32 v121, 0xbfb8aa3b, v121
	v_lshl_add_u64 v[132:133], v[128:129], 1, v[132:133]
	v_lshlrev_b64 v[128:129], 11, v[130:131]
	v_exp_f32_e32 v121, v121
	v_rcp_f32_e32 v131, v120
	v_add_f32_e32 v120, 1.0, v125
	v_mul_f32_e32 v125, 0xbfb8aa3b, v126
	v_exp_f32_e32 v125, v125
	v_pk_mul_f32 v[122:123], v[122:123], s[36:37] op_sel_hi:[1,0]
	v_add_f32_e32 v121, 1.0, v121
	v_mul_f32_e32 v122, 0xbfb8aa3b, v122
	v_mul_f32_e32 v124, 0xbfb8aa3b, v124
	v_exp_f32_e32 v122, v122
	v_rcp_f32_e32 v126, v121
	v_add_f32_e32 v121, 1.0, v125
	v_mul_f32_e32 v125, 0xbfb8aa3b, v127
	v_mul_f32_e32 v123, 0xbfb8aa3b, v123
	v_exp_f32_e32 v124, v124
	v_exp_f32_e32 v125, v125
	v_exp_f32_e32 v123, v123
	v_add_f32_e32 v122, 1.0, v122
	v_pk_mul_f32 v[112:113], v[112:113], s[36:37] op_sel_hi:[1,0]
	v_add_f32_e32 v124, 1.0, v124
	v_rcp_f32_e32 v127, v122
	v_add_f32_e32 v122, 1.0, v125
	v_add_f32_e32 v123, 1.0, v123
	v_pk_mul_f32 v[116:117], v[116:117], s[36:37] op_sel_hi:[1,0]
	v_mul_f32_e32 v112, 0xbfb8aa3b, v112
	v_rcp_f32_e32 v124, v124
	v_rcp_f32_e32 v120, v120
	v_rcp_f32_e32 v121, v121
	v_rcp_f32_e32 v122, v122
	v_rcp_f32_e32 v123, v123
	v_exp_f32_e32 v112, v112
	v_mul_f32_e32 v117, 0xbfb8aa3b, v117
	v_exp_f32_e32 v117, v117
	v_lshl_add_u64 v[128:129], v[132:133], 0, v[128:129]
	v_cvt_pk_bf16_f32 v120, v124, v120
	v_cvt_pk_bf16_f32 v121, v121, v122
	v_cvt_pk_bf16_f32 v122, v131, v126
	v_cvt_pk_bf16_f32 v123, v127, v123
	v_pk_mul_f32 v[118:119], v[118:119], s[36:37] op_sel_hi:[1,0]
	v_add_f32_e32 v112, 1.0, v112
	v_mul_f32_e32 v113, 0xbfb8aa3b, v113
	global_store_dwordx4 v[128:129], v[120:123], off nt
	v_exp_f32_e32 v113, v113
	v_pk_mul_f32 v[114:115], v[114:115], s[36:37] op_sel_hi:[1,0]
	v_rcp_f32_e32 v120, v112
	v_add_f32_e32 v112, 1.0, v117
	v_mul_f32_e32 v117, 0xbfb8aa3b, v118
	v_exp_f32_e32 v117, v117
	v_add_f32_e32 v113, 1.0, v113
	v_mul_f32_e32 v114, 0xbfb8aa3b, v114
	v_mul_f32_e32 v116, 0xbfb8aa3b, v116
	v_exp_f32_e32 v114, v114
	v_rcp_f32_e32 v118, v113
	v_add_f32_e32 v113, 1.0, v117
	v_mul_f32_e32 v117, 0xbfb8aa3b, v119
	v_mul_f32_e32 v115, 0xbfb8aa3b, v115
	v_exp_f32_e32 v116, v116
	v_exp_f32_e32 v117, v117
	v_exp_f32_e32 v115, v115
	v_add_f32_e32 v114, 1.0, v114
	v_pk_mul_f32 v[104:105], v[104:105], s[36:37] op_sel_hi:[1,0]
	v_add_f32_e32 v116, 1.0, v116
	v_rcp_f32_e32 v119, v114
	v_add_f32_e32 v114, 1.0, v117
	v_add_f32_e32 v115, 1.0, v115
	v_pk_mul_f32 v[108:109], v[108:109], s[36:37] op_sel_hi:[1,0]
	v_mul_f32_e32 v104, 0xbfb8aa3b, v104
	v_rcp_f32_e32 v116, v116
	v_rcp_f32_e32 v112, v112
	v_rcp_f32_e32 v113, v113
	v_rcp_f32_e32 v114, v114
	v_rcp_f32_e32 v115, v115
	v_exp_f32_e32 v104, v104
	v_mul_f32_e32 v109, 0xbfb8aa3b, v109
	v_exp_f32_e32 v109, v109
	v_cvt_pk_bf16_f32 v112, v116, v112
	v_cvt_pk_bf16_f32 v113, v113, v114
	v_cvt_pk_bf16_f32 v114, v120, v118
	v_cvt_pk_bf16_f32 v115, v119, v115
	v_pk_mul_f32 v[110:111], v[110:111], s[36:37] op_sel_hi:[1,0]
	v_add_f32_e32 v104, 1.0, v104
	v_mul_f32_e32 v105, 0xbfb8aa3b, v105
	global_store_dwordx4 v[128:129], v[112:115], off offset:256 nt
	v_exp_f32_e32 v105, v105
	v_pk_mul_f32 v[106:107], v[106:107], s[36:37] op_sel_hi:[1,0]
	v_rcp_f32_e32 v114, v104
	v_add_f32_e32 v104, 1.0, v109
	v_mul_f32_e32 v109, 0xbfb8aa3b, v110
	v_exp_f32_e32 v109, v109
	v_add_f32_e32 v105, 1.0, v105
	v_mul_f32_e32 v106, 0xbfb8aa3b, v106
	v_mul_f32_e32 v108, 0xbfb8aa3b, v108
	v_exp_f32_e32 v106, v106
	v_rcp_f32_e32 v110, v105
	v_add_f32_e32 v105, 1.0, v109
	v_mul_f32_e32 v109, 0xbfb8aa3b, v111
	v_mul_f32_e32 v107, 0xbfb8aa3b, v107
	v_exp_f32_e32 v108, v108
	v_exp_f32_e32 v109, v109
	v_exp_f32_e32 v107, v107
	v_add_f32_e32 v106, 1.0, v106
	v_pk_mul_f32 v[96:97], v[96:97], s[36:37] op_sel_hi:[1,0]
	v_add_f32_e32 v108, 1.0, v108
	v_rcp_f32_e32 v111, v106
	v_add_f32_e32 v106, 1.0, v109
	v_add_f32_e32 v107, 1.0, v107
	v_pk_mul_f32 v[100:101], v[100:101], s[36:37] op_sel_hi:[1,0]
	v_mul_f32_e32 v96, 0xbfb8aa3b, v96
	v_rcp_f32_e32 v108, v108
	v_rcp_f32_e32 v104, v104
	v_rcp_f32_e32 v105, v105
	v_rcp_f32_e32 v106, v106
	v_rcp_f32_e32 v107, v107
	v_exp_f32_e32 v96, v96
	v_mul_f32_e32 v101, 0xbfb8aa3b, v101
	v_or_b32_e32 v112, 16, v130
	v_exp_f32_e32 v101, v101
	v_ashrrev_i32_e32 v113, 31, v112
	v_lshlrev_b64 v[112:113], 11, v[112:113]
	v_lshl_add_u64 v[112:113], v[132:133], 0, v[112:113]
	v_cvt_pk_bf16_f32 v104, v108, v104
	v_cvt_pk_bf16_f32 v105, v105, v106
	v_cvt_pk_bf16_f32 v106, v114, v110
	v_cvt_pk_bf16_f32 v107, v111, v107
	v_pk_mul_f32 v[102:103], v[102:103], s[36:37] op_sel_hi:[1,0]
	v_add_f32_e32 v96, 1.0, v96
	v_mul_f32_e32 v97, 0xbfb8aa3b, v97
	global_store_dwordx4 v[112:113], v[104:107], off nt
	v_exp_f32_e32 v97, v97
	v_pk_mul_f32 v[98:99], v[98:99], s[36:37] op_sel_hi:[1,0]
	v_rcp_f32_e32 v104, v96
	v_add_f32_e32 v96, 1.0, v101
; __device__ __forceinline__ float fsigmoid(float v) { return __builtin_amdgcn_rcpf(1.f + __builtin_amdgcn_exp2f(-LOG2E * v)); }
; __device__ __forceinline__ u32x4 pack8(f32x4 a, f32x4 b) { u32x4 w; w.x = cvt_pk(a[0], a[1]); w.y = cvt_pk(a[2], a[3]); w.z = cvt_pk(b[0], b[1]); w.w = cvt_pk(b[2], b[3]); return w; }
;     __device__ __forceinline__ void operator()(EPI_ARGS) const {
;         const int row0 = u.pm * 256 + wr * 64 + fr, colt = u.pn * 256 + wc * 32 + 8 * fq, sec = u.pn >> 2, cs = colt - sec * 1024;
;         bf16_t* base = sec ? GA : GL;
; #pragma unroll
;         for (int ai = 0; ai < 2; ++ai)
; #pragma unroll
;             for (int m = 0; m < 4; ++m) { bf16_t* rowp = base + (size_t)(row0 + ai * 128 + m * 16) * DM + cs;
; #pragma unroll
;                 for (int bj = 0; bj < 2; ++bj) { f32x4 v0 = acc[ai][bj][m][0] * 0.03125f, v1 = acc[ai][bj][m][1] * 0.03125f;
; #pragma unroll
;                     for (int e = 0; e < 4; ++e) { v0[e] = fsigmoid(v0[e]); v1[e] = fsigmoid(v1[e]); }
;                     *(u32x4*)(rowp + bj * 128) = pack8(v0, v1); } }
	v_mul_f32_e32 v101, 0xbfb8aa3b, v102
	v_exp_f32_e32 v101, v101
	v_add_f32_e32 v97, 1.0, v97
	v_mul_f32_e32 v98, 0xbfb8aa3b, v98
	v_mul_f32_e32 v100, 0xbfb8aa3b, v100
	v_exp_f32_e32 v98, v98
	v_rcp_f32_e32 v102, v97
	v_add_f32_e32 v97, 1.0, v101
	v_mul_f32_e32 v101, 0xbfb8aa3b, v103
	v_mul_f32_e32 v99, 0xbfb8aa3b, v99
	v_exp_f32_e32 v100, v100
	v_exp_f32_e32 v101, v101
	v_exp_f32_e32 v99, v99
	v_add_f32_e32 v98, 1.0, v98
	v_pk_mul_f32 v[88:89], v[88:89], s[36:37] op_sel_hi:[1,0]
	v_add_f32_e32 v100, 1.0, v100
	v_rcp_f32_e32 v103, v98
	v_add_f32_e32 v98, 1.0, v101
	v_add_f32_e32 v99, 1.0, v99
	v_pk_mul_f32 v[92:93], v[92:93], s[36:37] op_sel_hi:[1,0]
	v_mul_f32_e32 v88, 0xbfb8aa3b, v88
	v_rcp_f32_e32 v100, v100
	v_rcp_f32_e32 v96, v96
	v_rcp_f32_e32 v97, v97
	v_rcp_f32_e32 v98, v98
	v_rcp_f32_e32 v99, v99
	v_exp_f32_e32 v88, v88
	v_mul_f32_e32 v93, 0xbfb8aa3b, v93
	v_exp_f32_e32 v93, v93
	v_cvt_pk_bf16_f32 v96, v100, v96
	v_cvt_pk_bf16_f32 v97, v97, v98
	v_cvt_pk_bf16_f32 v98, v104, v102
	v_cvt_pk_bf16_f32 v99, v103, v99
	v_pk_mul_f32 v[94:95], v[94:95], s[36:37] op_sel_hi:[1,0]
	v_add_f32_e32 v88, 1.0, v88
	v_mul_f32_e32 v89, 0xbfb8aa3b, v89
	global_store_dwordx4 v[112:113], v[96:99], off offset:256 nt
	v_exp_f32_e32 v89, v89
	v_pk_mul_f32 v[90:91], v[90:91], s[36:37] op_sel_hi:[1,0]
	v_rcp_f32_e32 v98, v88
	v_add_f32_e32 v88, 1.0, v93
	v_mul_f32_e32 v93, 0xbfb8aa3b, v94
	v_exp_f32_e32 v93, v93
	v_add_f32_e32 v89, 1.0, v89
	v_mul_f32_e32 v90, 0xbfb8aa3b, v90
	v_mul_f32_e32 v92, 0xbfb8aa3b, v92
	v_exp_f32_e32 v90, v90
	v_rcp_f32_e32 v94, v89
	v_add_f32_e32 v89, 1.0, v93
	v_mul_f32_e32 v93, 0xbfb8aa3b, v95
	v_mul_f32_e32 v91, 0xbfb8aa3b, v91
	v_exp_f32_e32 v92, v92
	v_exp_f32_e32 v93, v93
	v_exp_f32_e32 v91, v91
	v_add_f32_e32 v90, 1.0, v90
	v_pk_mul_f32 v[80:81], v[80:81], s[36:37] op_sel_hi:[1,0]
	v_add_f32_e32 v92, 1.0, v92
	v_rcp_f32_e32 v95, v90
	v_add_f32_e32 v90, 1.0, v93
	v_add_f32_e32 v91, 1.0, v91
	v_pk_mul_f32 v[84:85], v[84:85], s[36:37] op_sel_hi:[1,0]
	v_mul_f32_e32 v80, 0xbfb8aa3b, v80
	v_rcp_f32_e32 v92, v92
	v_rcp_f32_e32 v88, v88
	v_rcp_f32_e32 v89, v89
	v_rcp_f32_e32 v90, v90
	v_rcp_f32_e32 v91, v91
	v_exp_f32_e32 v80, v80
	v_mul_f32_e32 v85, 0xbfb8aa3b, v85
	v_or_b32_e32 v96, 32, v130
	v_exp_f32_e32 v85, v85
	v_ashrrev_i32_e32 v97, 31, v96
	v_lshlrev_b64 v[96:97], 11, v[96:97]
	v_lshl_add_u64 v[96:97], v[132:133], 0, v[96:97]
	v_cvt_pk_bf16_f32 v88, v92, v88
	v_cvt_pk_bf16_f32 v89, v89, v90
	v_cvt_pk_bf16_f32 v90, v98, v94
	v_cvt_pk_bf16_f32 v91, v95, v91
	v_pk_mul_f32 v[86:87], v[86:87], s[36:37] op_sel_hi:[1,0]
	v_add_f32_e32 v80, 1.0, v80
	v_mul_f32_e32 v81, 0xbfb8aa3b, v81
	global_store_dwordx4 v[96:97], v[88:91], off nt
	v_exp_f32_e32 v81, v81
	v_pk_mul_f32 v[82:83], v[82:83], s[36:37] op_sel_hi:[1,0]
	v_rcp_f32_e32 v88, v80
	v_add_f32_e32 v80, 1.0, v85
	v_mul_f32_e32 v85, 0xbfb8aa3b, v86
	v_exp_f32_e32 v85, v85
	v_add_f32_e32 v81, 1.0, v81
	v_mul_f32_e32 v82, 0xbfb8aa3b, v82
	v_mul_f32_e32 v84, 0xbfb8aa3b, v84
	v_exp_f32_e32 v82, v82
	v_rcp_f32_e32 v86, v81
	v_add_f32_e32 v81, 1.0, v85
	v_mul_f32_e32 v85, 0xbfb8aa3b, v87
	v_mul_f32_e32 v83, 0xbfb8aa3b, v83
	v_exp_f32_e32 v84, v84
	v_exp_f32_e32 v85, v85
	v_exp_f32_e32 v83, v83
	v_add_f32_e32 v82, 1.0, v82
	v_pk_mul_f32 v[72:73], v[72:73], s[36:37] op_sel_hi:[1,0]
	v_add_f32_e32 v84, 1.0, v84
	v_rcp_f32_e32 v87, v82
	v_add_f32_e32 v82, 1.0, v85
	v_add_f32_e32 v83, 1.0, v83
	v_pk_mul_f32 v[76:77], v[76:77], s[36:37] op_sel_hi:[1,0]
	v_mul_f32_e32 v72, 0xbfb8aa3b, v72
	v_rcp_f32_e32 v84, v84
	v_rcp_f32_e32 v80, v80
	v_rcp_f32_e32 v81, v81
	v_rcp_f32_e32 v82, v82
	v_rcp_f32_e32 v83, v83
	v_exp_f32_e32 v72, v72
	v_mul_f32_e32 v77, 0xbfb8aa3b, v77
	v_exp_f32_e32 v77, v77
	v_cvt_pk_bf16_f32 v80, v84, v80
	v_cvt_pk_bf16_f32 v81, v81, v82
	v_cvt_pk_bf16_f32 v82, v88, v86
	v_cvt_pk_bf16_f32 v83, v87, v83
	v_pk_mul_f32 v[78:79], v[78:79], s[36:37] op_sel_hi:[1,0]
	v_add_f32_e32 v72, 1.0, v72
	v_mul_f32_e32 v73, 0xbfb8aa3b, v73
	global_store_dwordx4 v[96:97], v[80:83], off offset:256 nt
	v_exp_f32_e32 v73, v73
	v_pk_mul_f32 v[74:75], v[74:75], s[36:37] op_sel_hi:[1,0]
	v_rcp_f32_e32 v82, v72
	v_add_f32_e32 v72, 1.0, v77
	v_mul_f32_e32 v77, 0xbfb8aa3b, v78
	v_exp_f32_e32 v77, v77
	v_add_f32_e32 v73, 1.0, v73
	v_mul_f32_e32 v74, 0xbfb8aa3b, v74
	v_mul_f32_e32 v76, 0xbfb8aa3b, v76
	v_exp_f32_e32 v74, v74
	v_rcp_f32_e32 v78, v73
	v_add_f32_e32 v73, 1.0, v77
	v_mul_f32_e32 v77, 0xbfb8aa3b, v79
	v_mul_f32_e32 v75, 0xbfb8aa3b, v75
	v_exp_f32_e32 v76, v76
	v_exp_f32_e32 v77, v77
	v_exp_f32_e32 v75, v75
	v_add_f32_e32 v74, 1.0, v74
	v_pk_mul_f32 v[64:65], v[64:65], s[36:37] op_sel_hi:[1,0]
	v_add_f32_e32 v76, 1.0, v76
	v_rcp_f32_e32 v79, v74
	v_add_f32_e32 v74, 1.0, v77
	v_add_f32_e32 v75, 1.0, v75
	v_pk_mul_f32 v[68:69], v[68:69], s[36:37] op_sel_hi:[1,0]
	v_mul_f32_e32 v64, 0xbfb8aa3b, v64
	v_rcp_f32_e32 v76, v76
	v_rcp_f32_e32 v72, v72
	v_rcp_f32_e32 v73, v73
	v_rcp_f32_e32 v74, v74
	v_rcp_f32_e32 v75, v75
	v_exp_f32_e32 v64, v64
	v_mul_f32_e32 v69, 0xbfb8aa3b, v69
	v_or_b32_e32 v80, 48, v130
	v_exp_f32_e32 v69, v69
	v_ashrrev_i32_e32 v81, 31, v80
	v_lshlrev_b64 v[80:81], 11, v[80:81]
	v_lshl_add_u64 v[80:81], v[132:133], 0, v[80:81]
	v_cvt_pk_bf16_f32 v72, v76, v72
	v_cvt_pk_bf16_f32 v73, v73, v74
	v_cvt_pk_bf16_f32 v74, v82, v78
	v_cvt_pk_bf16_f32 v75, v79, v75
	v_pk_mul_f32 v[70:71], v[70:71], s[36:37] op_sel_hi:[1,0]
	v_add_f32_e32 v64, 1.0, v64
	v_mul_f32_e32 v65, 0xbfb8aa3b, v65
	global_store_dwordx4 v[80:81], v[72:75], off nt
	v_exp_f32_e32 v65, v65
	v_pk_mul_f32 v[66:67], v[66:67], s[36:37] op_sel_hi:[1,0]
	v_rcp_f32_e32 v72, v64
	v_add_f32_e32 v64, 1.0, v69
; __device__ __forceinline__ float fsigmoid(float v) { return __builtin_amdgcn_rcpf(1.f + __builtin_amdgcn_exp2f(-LOG2E * v)); }
; __device__ __forceinline__ u32x4 pack8(f32x4 a, f32x4 b) { u32x4 w; w.x = cvt_pk(a[0], a[1]); w.y = cvt_pk(a[2], a[3]); w.z = cvt_pk(b[0], b[1]); w.w = cvt_pk(b[2], b[3]); return w; }
;     __device__ __forceinline__ void operator()(EPI_ARGS) const {
;         const int row0 = u.pm * 256 + wr * 64 + fr, colt = u.pn * 256 + wc * 32 + 8 * fq, sec = u.pn >> 2, cs = colt - sec * 1024;
;         bf16_t* base = sec ? GA : GL;
; #pragma unroll
;         for (int ai = 0; ai < 2; ++ai)
; #pragma unroll
;             for (int m = 0; m < 4; ++m) { bf16_t* rowp = base + (size_t)(row0 + ai * 128 + m * 16) * DM + cs;
; #pragma unroll
;                 for (int bj = 0; bj < 2; ++bj) { f32x4 v0 = acc[ai][bj][m][0] * 0.03125f, v1 = acc[ai][bj][m][1] * 0.03125f;
; #pragma unroll
;                     for (int e = 0; e < 4; ++e) { v0[e] = fsigmoid(v0[e]); v1[e] = fsigmoid(v1[e]); }
;                     *(u32x4*)(rowp + bj * 128) = pack8(v0, v1); } }
	v_mul_f32_e32 v69, 0xbfb8aa3b, v70
	v_exp_f32_e32 v69, v69
	v_add_f32_e32 v65, 1.0, v65
	v_mul_f32_e32 v66, 0xbfb8aa3b, v66
	v_mul_f32_e32 v68, 0xbfb8aa3b, v68
	v_exp_f32_e32 v66, v66
	v_rcp_f32_e32 v70, v65
	v_add_f32_e32 v65, 1.0, v69
	v_mul_f32_e32 v69, 0xbfb8aa3b, v71
	v_mul_f32_e32 v67, 0xbfb8aa3b, v67
	v_exp_f32_e32 v68, v68
	v_exp_f32_e32 v69, v69
	v_exp_f32_e32 v67, v67
	v_add_f32_e32 v66, 1.0, v66
	v_pk_mul_f32 v[56:57], v[56:57], s[36:37] op_sel_hi:[1,0]
	v_add_f32_e32 v68, 1.0, v68
	v_rcp_f32_e32 v71, v66
	v_add_f32_e32 v66, 1.0, v69
	v_add_f32_e32 v67, 1.0, v67
	v_pk_mul_f32 v[60:61], v[60:61], s[36:37] op_sel_hi:[1,0]
	v_mul_f32_e32 v56, 0xbfb8aa3b, v56
	v_rcp_f32_e32 v68, v68
	v_rcp_f32_e32 v64, v64
	v_rcp_f32_e32 v65, v65
	v_rcp_f32_e32 v66, v66
	v_rcp_f32_e32 v67, v67
	v_exp_f32_e32 v56, v56
	v_mul_f32_e32 v61, 0xbfb8aa3b, v61
	v_exp_f32_e32 v61, v61
	v_cvt_pk_bf16_f32 v64, v68, v64
	v_cvt_pk_bf16_f32 v65, v65, v66
	v_cvt_pk_bf16_f32 v66, v72, v70
	v_cvt_pk_bf16_f32 v67, v71, v67
	v_pk_mul_f32 v[62:63], v[62:63], s[36:37] op_sel_hi:[1,0]
	v_add_f32_e32 v56, 1.0, v56
	v_mul_f32_e32 v57, 0xbfb8aa3b, v57
	global_store_dwordx4 v[80:81], v[64:67], off offset:256 nt
	v_exp_f32_e32 v57, v57
	v_pk_mul_f32 v[58:59], v[58:59], s[36:37] op_sel_hi:[1,0]
	v_rcp_f32_e32 v66, v56
	v_add_f32_e32 v56, 1.0, v61
	v_mul_f32_e32 v61, 0xbfb8aa3b, v62
	v_exp_f32_e32 v61, v61
	v_mul_f32_e32 v60, 0xbfb8aa3b, v60
	v_add_f32_e32 v57, 1.0, v57
	v_mul_f32_e32 v58, 0xbfb8aa3b, v58
	v_exp_f32_e32 v60, v60
	v_exp_f32_e32 v58, v58
	v_rcp_f32_e32 v62, v57
	v_add_f32_e32 v57, 1.0, v61
	v_mul_f32_e32 v61, 0xbfb8aa3b, v63
	v_mul_f32_e32 v59, 0xbfb8aa3b, v59
	v_exp_f32_e32 v61, v61
	v_exp_f32_e32 v59, v59
	v_add_f32_e32 v60, 1.0, v60
	v_add_f32_e32 v58, 1.0, v58
	v_pk_mul_f32 v[48:49], v[48:49], s[36:37] op_sel_hi:[1,0]
	v_rcp_f32_e32 v60, v60
	v_rcp_f32_e32 v56, v56
	v_rcp_f32_e32 v63, v58
	v_add_f32_e32 v58, 1.0, v61
	v_add_f32_e32 v59, 1.0, v59
	v_pk_mul_f32 v[52:53], v[52:53], s[36:37] op_sel_hi:[1,0]
	v_mul_f32_e32 v48, 0xbfb8aa3b, v48
	v_rcp_f32_e32 v57, v57
	v_rcp_f32_e32 v58, v58
	v_rcp_f32_e32 v59, v59
	v_exp_f32_e32 v48, v48
	v_mul_f32_e32 v53, 0xbfb8aa3b, v53
	v_exp_f32_e32 v53, v53
	s_mov_b32 s3, 0x40000
	v_cvt_pk_bf16_f32 v56, v60, v56
	v_add_co_u32_e32 v60, vcc, s3, v128
	v_cvt_pk_bf16_f32 v57, v57, v58
	v_cvt_pk_bf16_f32 v58, v66, v62
	v_cvt_pk_bf16_f32 v59, v63, v59
	v_addc_co_u32_e32 v61, vcc, 0, v129, vcc
	v_pk_mul_f32 v[54:55], v[54:55], s[36:37] op_sel_hi:[1,0]
	v_add_f32_e32 v48, 1.0, v48
	v_mul_f32_e32 v49, 0xbfb8aa3b, v49
	global_store_dwordx4 v[60:61], v[56:59], off nt
	v_exp_f32_e32 v49, v49
	v_pk_mul_f32 v[50:51], v[50:51], s[36:37] op_sel_hi:[1,0]
	v_rcp_f32_e32 v56, v48
	v_add_f32_e32 v48, 1.0, v53
	v_mul_f32_e32 v53, 0xbfb8aa3b, v54
	v_exp_f32_e32 v53, v53
	v_add_f32_e32 v49, 1.0, v49
	v_mul_f32_e32 v50, 0xbfb8aa3b, v50
	v_mul_f32_e32 v52, 0xbfb8aa3b, v52
	v_exp_f32_e32 v50, v50
	v_rcp_f32_e32 v54, v49
	v_add_f32_e32 v49, 1.0, v53
	v_mul_f32_e32 v53, 0xbfb8aa3b, v55
	v_mul_f32_e32 v51, 0xbfb8aa3b, v51
	v_exp_f32_e32 v52, v52
	v_exp_f32_e32 v53, v53
	v_exp_f32_e32 v51, v51
	v_add_f32_e32 v50, 1.0, v50
	v_pk_mul_f32 v[40:41], v[40:41], s[36:37] op_sel_hi:[1,0]
	v_add_f32_e32 v52, 1.0, v52
	v_rcp_f32_e32 v55, v50
	v_add_f32_e32 v50, 1.0, v53
	v_add_f32_e32 v51, 1.0, v51
	v_pk_mul_f32 v[44:45], v[44:45], s[36:37] op_sel_hi:[1,0]
	v_mul_f32_e32 v40, 0xbfb8aa3b, v40
	v_rcp_f32_e32 v52, v52
	v_rcp_f32_e32 v48, v48
	v_rcp_f32_e32 v49, v49
	v_rcp_f32_e32 v50, v50
	v_rcp_f32_e32 v51, v51
	v_exp_f32_e32 v40, v40
	v_mul_f32_e32 v45, 0xbfb8aa3b, v45
	v_exp_f32_e32 v45, v45
	s_mov_b64 s[46:47], 0x40000
	v_lshl_add_u64 v[64:65], v[128:129], 0, s[46:47]
	v_cvt_pk_bf16_f32 v48, v52, v48
	v_cvt_pk_bf16_f32 v49, v49, v50
	v_cvt_pk_bf16_f32 v50, v56, v54
	v_cvt_pk_bf16_f32 v51, v55, v51
	v_pk_mul_f32 v[46:47], v[46:47], s[36:37] op_sel_hi:[1,0]
	v_add_f32_e32 v40, 1.0, v40
	v_mul_f32_e32 v41, 0xbfb8aa3b, v41
	global_store_dwordx4 v[64:65], v[48:51], off offset:256 nt
	v_exp_f32_e32 v41, v41
	v_pk_mul_f32 v[42:43], v[42:43], s[36:37] op_sel_hi:[1,0]
	v_rcp_f32_e32 v50, v40
	v_add_f32_e32 v40, 1.0, v45
	v_mul_f32_e32 v45, 0xbfb8aa3b, v46
	v_exp_f32_e32 v45, v45
	v_mul_f32_e32 v44, 0xbfb8aa3b, v44
	v_add_f32_e32 v41, 1.0, v41
	v_mul_f32_e32 v42, 0xbfb8aa3b, v42
	v_exp_f32_e32 v44, v44
	v_exp_f32_e32 v42, v42
	v_rcp_f32_e32 v46, v41
	v_add_f32_e32 v41, 1.0, v45
	v_mul_f32_e32 v45, 0xbfb8aa3b, v47
	v_mul_f32_e32 v43, 0xbfb8aa3b, v43
	v_exp_f32_e32 v45, v45
	v_exp_f32_e32 v43, v43
	v_add_f32_e32 v44, 1.0, v44
	v_add_f32_e32 v42, 1.0, v42
	v_pk_mul_f32 v[32:33], v[32:33], s[36:37] op_sel_hi:[1,0]
	v_rcp_f32_e32 v44, v44
	v_rcp_f32_e32 v40, v40
	v_rcp_f32_e32 v47, v42
	v_add_f32_e32 v42, 1.0, v45
	v_add_f32_e32 v43, 1.0, v43
	v_pk_mul_f32 v[36:37], v[36:37], s[36:37] op_sel_hi:[1,0]
	v_mul_f32_e32 v32, 0xbfb8aa3b, v32
	v_rcp_f32_e32 v41, v41
	v_rcp_f32_e32 v42, v42
	v_rcp_f32_e32 v43, v43
	v_exp_f32_e32 v32, v32
	v_mul_f32_e32 v37, 0xbfb8aa3b, v37
	v_exp_f32_e32 v37, v37
	s_mov_b32 s3, 0x48000
	v_cvt_pk_bf16_f32 v40, v44, v40
	v_add_co_u32_e32 v44, vcc, s3, v128
	v_cvt_pk_bf16_f32 v41, v41, v42
	v_cvt_pk_bf16_f32 v42, v50, v46
	v_cvt_pk_bf16_f32 v43, v47, v43
	v_addc_co_u32_e32 v45, vcc, 0, v129, vcc
	v_pk_mul_f32 v[38:39], v[38:39], s[36:37] op_sel_hi:[1,0]
	v_add_f32_e32 v32, 1.0, v32
	v_mul_f32_e32 v33, 0xbfb8aa3b, v33
	global_store_dwordx4 v[44:45], v[40:43], off nt
	v_exp_f32_e32 v33, v33
	v_pk_mul_f32 v[34:35], v[34:35], s[36:37] op_sel_hi:[1,0]
	v_rcp_f32_e32 v40, v32
	v_add_f32_e32 v32, 1.0, v37
	v_mul_f32_e32 v37, 0xbfb8aa3b, v38
	v_exp_f32_e32 v37, v37
; __device__ __forceinline__ float fsigmoid(float v) { return __builtin_amdgcn_rcpf(1.f + __builtin_amdgcn_exp2f(-LOG2E * v)); }
; __device__ __forceinline__ u32x4 pack8(f32x4 a, f32x4 b) { u32x4 w; w.x = cvt_pk(a[0], a[1]); w.y = cvt_pk(a[2], a[3]); w.z = cvt_pk(b[0], b[1]); w.w = cvt_pk(b[2], b[3]); return w; }
;     __device__ __forceinline__ void operator()(EPI_ARGS) const {
;         const int row0 = u.pm * 256 + wr * 64 + fr, colt = u.pn * 256 + wc * 32 + 8 * fq, sec = u.pn >> 2, cs = colt - sec * 1024;
;         bf16_t* base = sec ? GA : GL;
; #pragma unroll
;         for (int ai = 0; ai < 2; ++ai)
; #pragma unroll
;             for (int m = 0; m < 4; ++m) { bf16_t* rowp = base + (size_t)(row0 + ai * 128 + m * 16) * DM + cs;
; #pragma unroll
;                 for (int bj = 0; bj < 2; ++bj) { f32x4 v0 = acc[ai][bj][m][0] * 0.03125f, v1 = acc[ai][bj][m][1] * 0.03125f;
; #pragma unroll
;                     for (int e = 0; e < 4; ++e) { v0[e] = fsigmoid(v0[e]); v1[e] = fsigmoid(v1[e]); }
;                     *(u32x4*)(rowp + bj * 128) = pack8(v0, v1); } }
	v_add_f32_e32 v33, 1.0, v33
	v_mul_f32_e32 v34, 0xbfb8aa3b, v34
	v_mul_f32_e32 v36, 0xbfb8aa3b, v36
	v_exp_f32_e32 v34, v34
	v_rcp_f32_e32 v38, v33
	v_add_f32_e32 v33, 1.0, v37
	v_mul_f32_e32 v37, 0xbfb8aa3b, v39
	v_mul_f32_e32 v35, 0xbfb8aa3b, v35
	v_exp_f32_e32 v36, v36
	v_exp_f32_e32 v37, v37
	v_exp_f32_e32 v35, v35
	v_add_f32_e32 v34, 1.0, v34
	v_pk_mul_f32 v[24:25], v[24:25], s[36:37] op_sel_hi:[1,0]
	v_add_f32_e32 v36, 1.0, v36
	v_rcp_f32_e32 v39, v34
	v_add_f32_e32 v34, 1.0, v37
	v_add_f32_e32 v35, 1.0, v35
	v_pk_mul_f32 v[28:29], v[28:29], s[36:37] op_sel_hi:[1,0]
	v_mul_f32_e32 v24, 0xbfb8aa3b, v24
	v_rcp_f32_e32 v36, v36
	v_rcp_f32_e32 v32, v32
	v_rcp_f32_e32 v33, v33
	v_rcp_f32_e32 v34, v34
	v_rcp_f32_e32 v35, v35
	v_exp_f32_e32 v24, v24
	v_mul_f32_e32 v29, 0xbfb8aa3b, v29
	v_exp_f32_e32 v29, v29
	s_mov_b64 s[46:47], 0x48000
	v_lshl_add_u64 v[48:49], v[128:129], 0, s[46:47]
	v_cvt_pk_bf16_f32 v32, v36, v32
	v_cvt_pk_bf16_f32 v33, v33, v34
	v_cvt_pk_bf16_f32 v34, v40, v38
	v_cvt_pk_bf16_f32 v35, v39, v35
	v_pk_mul_f32 v[30:31], v[30:31], s[36:37] op_sel_hi:[1,0]
	v_add_f32_e32 v24, 1.0, v24
	v_mul_f32_e32 v25, 0xbfb8aa3b, v25
	global_store_dwordx4 v[48:49], v[32:35], off offset:256 nt
	v_exp_f32_e32 v25, v25
	v_pk_mul_f32 v[26:27], v[26:27], s[36:37] op_sel_hi:[1,0]
	v_rcp_f32_e32 v34, v24
	v_add_f32_e32 v24, 1.0, v29
	v_mul_f32_e32 v29, 0xbfb8aa3b, v30
	v_exp_f32_e32 v29, v29
	v_mul_f32_e32 v28, 0xbfb8aa3b, v28
	v_add_f32_e32 v25, 1.0, v25
	v_mul_f32_e32 v26, 0xbfb8aa3b, v26
	v_exp_f32_e32 v28, v28
	v_exp_f32_e32 v26, v26
	v_rcp_f32_e32 v30, v25
	v_add_f32_e32 v25, 1.0, v29
	v_mul_f32_e32 v29, 0xbfb8aa3b, v31
	v_mul_f32_e32 v27, 0xbfb8aa3b, v27
	v_exp_f32_e32 v29, v29
	v_exp_f32_e32 v27, v27
	v_add_f32_e32 v28, 1.0, v28
	v_add_f32_e32 v26, 1.0, v26
	v_pk_mul_f32 v[16:17], v[16:17], s[36:37] op_sel_hi:[1,0]
	v_rcp_f32_e32 v28, v28
	v_rcp_f32_e32 v24, v24
	v_rcp_f32_e32 v31, v26
	v_add_f32_e32 v26, 1.0, v29
	v_add_f32_e32 v27, 1.0, v27
	v_pk_mul_f32 v[20:21], v[20:21], s[36:37] op_sel_hi:[1,0]
	v_mul_f32_e32 v16, 0xbfb8aa3b, v16
	v_rcp_f32_e32 v25, v25
	v_rcp_f32_e32 v26, v26
	v_rcp_f32_e32 v27, v27
	v_exp_f32_e32 v16, v16
	v_mul_f32_e32 v21, 0xbfb8aa3b, v21
	v_exp_f32_e32 v21, v21
	s_mov_b32 s3, 0x50000
	v_cvt_pk_bf16_f32 v24, v28, v24
	v_add_co_u32_e32 v28, vcc, s3, v128
	v_cvt_pk_bf16_f32 v25, v25, v26
	v_cvt_pk_bf16_f32 v26, v34, v30
	v_cvt_pk_bf16_f32 v27, v31, v27
	v_addc_co_u32_e32 v29, vcc, 0, v129, vcc
	v_pk_mul_f32 v[22:23], v[22:23], s[36:37] op_sel_hi:[1,0]
	v_add_f32_e32 v16, 1.0, v16
	v_mul_f32_e32 v17, 0xbfb8aa3b, v17
	global_store_dwordx4 v[28:29], v[24:27], off nt
	v_exp_f32_e32 v17, v17
	v_pk_mul_f32 v[18:19], v[18:19], s[36:37] op_sel_hi:[1,0]
	v_rcp_f32_e32 v24, v16
	v_add_f32_e32 v16, 1.0, v21
	v_mul_f32_e32 v21, 0xbfb8aa3b, v22
	v_exp_f32_e32 v21, v21
	v_add_f32_e32 v17, 1.0, v17
	v_mul_f32_e32 v18, 0xbfb8aa3b, v18
	v_mul_f32_e32 v20, 0xbfb8aa3b, v20
	v_exp_f32_e32 v18, v18
	v_rcp_f32_e32 v22, v17
	v_add_f32_e32 v17, 1.0, v21
	v_mul_f32_e32 v21, 0xbfb8aa3b, v23
	v_mul_f32_e32 v19, 0xbfb8aa3b, v19
	v_exp_f32_e32 v20, v20
	v_exp_f32_e32 v21, v21
	v_exp_f32_e32 v19, v19
	v_add_f32_e32 v18, 1.0, v18
	v_pk_mul_f32 v[8:9], v[8:9], s[36:37] op_sel_hi:[1,0]
	v_add_f32_e32 v20, 1.0, v20
	v_rcp_f32_e32 v23, v18
	v_add_f32_e32 v18, 1.0, v21
	v_add_f32_e32 v19, 1.0, v19
	v_pk_mul_f32 v[12:13], v[12:13], s[36:37] op_sel_hi:[1,0]
	v_mul_f32_e32 v8, 0xbfb8aa3b, v8
	v_rcp_f32_e32 v20, v20
	v_rcp_f32_e32 v16, v16
	v_rcp_f32_e32 v17, v17
	v_rcp_f32_e32 v18, v18
	v_rcp_f32_e32 v19, v19
	v_exp_f32_e32 v8, v8
	v_mul_f32_e32 v13, 0xbfb8aa3b, v13
	v_exp_f32_e32 v13, v13
	s_mov_b64 s[46:47], 0x50000
	v_lshl_add_u64 v[32:33], v[128:129], 0, s[46:47]
	v_cvt_pk_bf16_f32 v16, v20, v16
	v_cvt_pk_bf16_f32 v17, v17, v18
	v_cvt_pk_bf16_f32 v18, v24, v22
	v_cvt_pk_bf16_f32 v19, v23, v19
	v_pk_mul_f32 v[14:15], v[14:15], s[36:37] op_sel_hi:[1,0]
	v_add_f32_e32 v8, 1.0, v8
	v_mul_f32_e32 v9, 0xbfb8aa3b, v9
	global_store_dwordx4 v[32:33], v[16:19], off offset:256 nt
	v_exp_f32_e32 v9, v9
	v_pk_mul_f32 v[10:11], v[10:11], s[36:37] op_sel_hi:[1,0]
	v_rcp_f32_e32 v18, v8
	v_add_f32_e32 v8, 1.0, v13
	v_mul_f32_e32 v13, 0xbfb8aa3b, v14
	v_exp_f32_e32 v13, v13
	v_mul_f32_e32 v12, 0xbfb8aa3b, v12
	v_add_f32_e32 v9, 1.0, v9
	v_mul_f32_e32 v10, 0xbfb8aa3b, v10
	v_exp_f32_e32 v12, v12
	v_exp_f32_e32 v10, v10
	v_rcp_f32_e32 v14, v9
	v_add_f32_e32 v9, 1.0, v13
	v_mul_f32_e32 v13, 0xbfb8aa3b, v15
	v_mul_f32_e32 v11, 0xbfb8aa3b, v11
	v_exp_f32_e32 v13, v13
	v_exp_f32_e32 v11, v11
	v_add_f32_e32 v12, 1.0, v12
	v_add_f32_e32 v10, 1.0, v10
	v_pk_mul_f32 v[0:1], v[0:1], s[36:37] op_sel_hi:[1,0]
	v_rcp_f32_e32 v12, v12
	v_rcp_f32_e32 v8, v8
	v_rcp_f32_e32 v15, v10
	v_add_f32_e32 v10, 1.0, v13
	v_add_f32_e32 v11, 1.0, v11
	v_pk_mul_f32 v[4:5], v[4:5], s[36:37] op_sel_hi:[1,0]
	v_mul_f32_e32 v0, 0xbfb8aa3b, v0
	v_rcp_f32_e32 v9, v9
	v_rcp_f32_e32 v10, v10
	v_rcp_f32_e32 v11, v11
	v_exp_f32_e32 v0, v0
	v_mul_f32_e32 v5, 0xbfb8aa3b, v5
	v_exp_f32_e32 v5, v5
	s_mov_b32 s3, 0x58000
	v_cvt_pk_bf16_f32 v8, v12, v8
	v_add_co_u32_e32 v12, vcc, s3, v128
	v_cvt_pk_bf16_f32 v9, v9, v10
	v_cvt_pk_bf16_f32 v10, v18, v14
	v_cvt_pk_bf16_f32 v11, v15, v11
	v_addc_co_u32_e32 v13, vcc, 0, v129, vcc
	v_pk_mul_f32 v[6:7], v[6:7], s[36:37] op_sel_hi:[1,0]
	v_add_f32_e32 v0, 1.0, v0
	v_mul_f32_e32 v1, 0xbfb8aa3b, v1
	global_store_dwordx4 v[12:13], v[8:11], off nt
	v_exp_f32_e32 v1, v1
	v_pk_mul_f32 v[2:3], v[2:3], s[36:37] op_sel_hi:[1,0]
	v_rcp_f32_e32 v8, v0
	v_add_f32_e32 v0, 1.0, v5
	v_mul_f32_e32 v5, 0xbfb8aa3b, v6
	v_exp_f32_e32 v5, v5
	v_add_f32_e32 v1, 1.0, v1
	v_mul_f32_e32 v2, 0xbfb8aa3b, v2
	v_mul_f32_e32 v4, 0xbfb8aa3b, v4
	v_exp_f32_e32 v2, v2
	v_rcp_f32_e32 v6, v1
	v_add_f32_e32 v1, 1.0, v5
	v_mul_f32_e32 v5, 0xbfb8aa3b, v7
	v_mul_f32_e32 v3, 0xbfb8aa3b, v3
	v_exp_f32_e32 v4, v4
	v_exp_f32_e32 v5, v5
	v_exp_f32_e32 v3, v3
	v_add_f32_e32 v2, 1.0, v2
	v_add_f32_e32 v4, 1.0, v4
	v_rcp_f32_e32 v7, v2
	v_add_f32_e32 v2, 1.0, v5
	v_add_f32_e32 v3, 1.0, v3
	v_rcp_f32_e32 v4, v4
	v_rcp_f32_e32 v0, v0
	v_rcp_f32_e32 v1, v1
	v_rcp_f32_e32 v2, v2
	v_rcp_f32_e32 v3, v3
	s_mov_b64 s[46:47], 0x58000
	v_readlane_b32 s60, v247, 29
	v_lshl_add_u64 v[16:17], v[128:129], 0, s[46:47]
	v_cvt_pk_bf16_f32 v0, v4, v0
	v_cvt_pk_bf16_f32 v1, v1, v2
	v_cvt_pk_bf16_f32 v2, v8, v6
	v_cvt_pk_bf16_f32 v3, v7, v3
	s_andn2_b64 vcc, exec, s[40:41]
	s_mov_b64 s[40:41], -1
	v_readlane_b32 s61, v247, 30
	global_store_dwordx4 v[16:17], v[0:3], off offset:256 nt
	s_cbranch_vccnz .LBB0_336
	s_andn2_b64 vcc, exec, s[0:1]
	s_cbranch_vccnz .LBB0_335
	s_barrier
	s_branch .LBB0_335
